# attention: static s_setprio 1 for waves 4-7 (younger half) during the attention phase
# baseline (speedup 1.0000x reference)
; #define WAIT_BAR(N) asm volatile("s_waitcnt vmcnt(" #N ") lgkmcnt(0)\n\ts_barrier":::"memory")
;   #define DMA_K(t,slot) glds16(ksrc+(long)(t)*4096,(unsigned)__builtin_amdgcn_readfirstlane(kdst+(slot)))
;   #define DMA_V(t,slot) do{ glds16(vsrc+(long)(t)*8192,(unsigned)__builtin_amdgcn_readfirstlane(vdst+2*(slot))); glds16(vsrc+(long)(t)*8192+4096,(unsigned)__builtin_amdgcn_readfirstlane(vdst+2*(slot)+8192)); }while(0)
;   #define CMASK(P0,P1,t) do{int jb_=(t)-(NT-4); if(jb_>=-2&&(32*wid-64*jb_<176||64*jb_+63>32*wid))cmask(P0,P1,jb_,qrel,hi,btab);}while(0)
;   #define CMASK(P0,P1,t) do{}while(0)
; template<int THRL> __device__ __forceinline__ void attn_unit(int b,int hc,int qb,const bf16*Q,const bf16*__restrict__ K,const bf16*__restrict__ V,bf16*O,char*shm){
;   const int tid=threadIdx.x,lane=tid&63,r32=lane&31,hi=lane>>5; const int wid=__builtin_amdgcn_readfirstlane(tid>>6);
;   const long rowbase=(long)b*SEQ; const int q0=qb*QB;
;   const bf16*Qw=Q+(rowbase+q0+wid*QBLK)*DM+hc*D;
;   const lds_cfptr btab=(lds_cfptr)((lds_cptr)shm+LDS_BIAS);
;   const unsigned lds0=(unsigned)(uintptr_t)shm;
;   float*wsf=(float*)(shm+LDS_WS)+wid*64;
;   const bf16*ksrc=K+(long)((b*16+hc)*128)*4096+wid*512+lane*8;
;   const bf16*vsrc=V+(long)((b*8+(hc>>1))*128)*8192+wid*512+lane*8;
;   const unsigned kdst=lds0+LDS_K+wid*1024, vdst=lds0+LDS_V+wid*1024;
;     ...
;   const int vb0=(int)(lds0+LDS_V)+((lane>>4)&1)*32+(lane&3)*8+(4*hi+((lane&15)>>2))*64;
;   const char*Kbase=shm+LDS_K; bf16x8 kf[8];
;   const lds_cptr shm3=(lds_cptr)shm; const lds_cptr kp0=shm3+LDS_K+hi*1024+r32*16; const lds_cptr vp0=shm3+LDS_V+((lane>>4)&1)*32+(lane&3)*8+(4*hi+((lane&15)>>2))*64;
;   const int NT=(q0+QB)/KVBLK;
;   DMA_K(0,0);DMA_V(0,0);DMA_K(1,SLOTB);
;   bf16x8 qr[4];
;   #pragma unroll
;   for(int d0=0;d0<4;++d0)qr[d0]=*reinterpret_cast<const bf16x8*>(&Qw[(long)r32*DM+d0*16+hi*8]);
;   float mhat=0.f,l_reg=0.f;f32x16 o[4];o[0]=f32x16{};o[1]=f32x16{};o[2]=f32x16{};o[3]=f32x16{};
;   const f32x16 zero16=f32x16{};
;   const int qrel=wid*QBLK+r32;
;     ...
;   bool resc=false;
;     ...
;   f32x16 pA0,pA1,pB0,pB1;
;   int sl_prev=0,sl_cur=0,sl_next=SLOTB;
;     ...
;   DMA_K(2,2*SLOTB);
;   WAIT_BAR(4);
;   qkt(pA0,pA1,Kbase,qr,zero16,r32,hi);asm volatile("s_nop 15\n\ts_nop 7":"+v"(pA0),"+v"(pA1));CMASK(pA0,pA1,0);
.LBB0_1240:
	s_ashr_i32 s22, s83, 4
	v_readfirstlane_b32 s87, v208
	s_ashr_i32 s23, s22, 31
	s_lshl_b32 s18, s82, 8
	s_and_b32 s84, s83, 15
	s_lshr_b32 s85, s87, 6
	s_cmp_ge_u32 s85, 4
	s_cbranch_scc0 .Lprio_skip
	s_setprio 1
.Lprio_skip:
	s_lshl_b64 s[0:1], s[22:23], 13
	s_ashr_i32 s12, s18, 31
	s_add_u32 s0, s0, s18
	s_addc_u32 s1, s1, s12
	s_lshl_b32 s88, s85, 5
	s_add_u32 s48, s0, s88
	s_addc_u32 s49, s1, 0
	s_lshl_b64 s[0:1], s[48:49], 11
	s_add_u32 s0, s33, s0
	s_addc_u32 s1, s58, s1
	s_lshl_b32 s21, s83, 6
	s_lshl_b32 s12, s84, 7
	s_add_u32 s30, s0, s12
	s_addc_u32 s31, s1, 0
	s_lshl_b32 s0, s22, 11
	s_or_b32 s0, s12, s0
	s_ashr_i32 s1, s0, 31
	s_lshl_b64 s[0:1], s[0:1], 13
	s_add_u32 s19, s59, s0
	s_addc_u32 s23, s60, s1
	s_lshl_b32 s12, s85, 9
	s_lshl_b64 s[0:1], s[12:13], 1
	s_add_u32 s36, s19, s0
	s_addc_u32 s37, s23, s1
	s_lshl_b32 s19, s22, 10
	s_and_b32 s21, s21, 0x380
	s_or_b32 s22, s21, s19
	s_ashr_i32 s23, s22, 31
	s_lshl_b64 s[22:23], s[22:23], 14
	s_add_u32 s12, s61, s22
	s_addc_u32 s23, s62, s23
	s_add_u32 s22, s12, s0
	s_addc_u32 s23, s23, s1
	s_lshl_b32 s12, s85, 10
	s_cmp_lg_u32 0, -1
	v_lshl_add_u64 v[32:33], s[22:23], 0, v[196:197]
	s_cselect_b32 s22, 0, 0
	v_lshl_add_u64 v[202:203], s[36:37], 0, v[196:197]
	s_add_i32 s89, s12, s22
	s_mov_b32 s22, m0
	s_mov_b32 m0, s89
	s_nop 0
	global_load_lds_dwordx4 v[202:203], off
	s_mov_b32 m0, s22
	s_add_i32 s90, s89, 0x6000
	s_mov_b32 s22, m0
	s_mov_b32 m0, s90
	s_nop 0
	global_load_lds_dwordx4 v[32:33], off
	s_mov_b32 m0, s22
	v_lshl_add_u64 v[0:1], v[32:33], 0, s[14:15]
	s_add_i32 s22, s89, 0x8000
	s_mov_b32 s23, m0
	s_mov_b32 m0, s22
	s_nop 0
	global_load_lds_dwordx4 v[0:1], off
	s_mov_b32 m0, s23
	v_lshl_add_u64 v[0:1], v[202:203], 0, s[14:15]
	s_add_i32 s22, s89, 0x2000
	s_mov_b32 s23, m0
	s_mov_b32 m0, s22
	s_nop 0
	global_load_lds_dwordx4 v[0:1], off
	s_mov_b32 m0, s23
	global_load_dwordx4 v[156:159], v231, s[30:31]
	global_load_dwordx4 v[152:155], v231, s[30:31] offset:32
	global_load_dwordx4 v[144:147], v231, s[30:31] offset:64
	global_load_dwordx4 v[136:139], v231, s[30:31] offset:96
	v_lshl_add_u64 v[0:1], v[202:203], 0, s[16:17]
	s_add_i32 s22, s89, 0x4000
	s_mov_b32 s23, m0
	s_mov_b32 m0, s22
	s_nop 0
	global_load_lds_dwordx4 v[0:1], off
	s_mov_b32 m0, s23
	s_waitcnt vmcnt(4) lgkmcnt(0)
	s_barrier
	ds_read_b128 v[0:3], v213
	ds_read_b128 v[4:7], v213 offset:512
	ds_read_b128 v[34:37], v213 offset:2048
	ds_read_b128 v[38:41], v213 offset:2560
	s_add_i32 s22, s18, 0x100
	s_ashr_i32 s91, s22, 6
	v_or_b32_e32 v234, s88, v212
	s_cmp_gt_i32 s91, 6
	s_waitcnt vmcnt(3) lgkmcnt(3)
	v_mfma_f32_32x32x16_bf16 v[16:31], v[0:3], v[156:159], 0
	s_waitcnt lgkmcnt(2)
	v_mfma_f32_32x32x16_bf16 v[0:15], v[4:7], v[156:159], 0
	s_waitcnt vmcnt(2) lgkmcnt(1)
	v_mfma_f32_32x32x16_bf16 v[16:31], v[34:37], v[152:155], v[16:31]
	s_waitcnt lgkmcnt(0)
	v_mfma_f32_32x32x16_bf16 v[0:15], v[38:41], v[152:155], v[0:15]
	ds_read_b128 v[34:37], v213 offset:4096
	ds_read_b128 v[38:41], v213 offset:4608
	s_waitcnt vmcnt(1) lgkmcnt(1)
	v_mfma_f32_32x32x16_bf16 v[16:31], v[34:37], v[144:147], v[16:31]
	s_waitcnt lgkmcnt(0)
	v_mfma_f32_32x32x16_bf16 v[0:15], v[38:41], v[144:147], v[0:15]
	ds_read_b128 v[34:37], v213 offset:6144
	ds_read_b128 v[38:41], v213 offset:6656
	s_waitcnt vmcnt(0) lgkmcnt(1)
	v_mfma_f32_32x32x16_bf16 v[16:31], v[34:37], v[136:139], v[16:31]
	s_waitcnt lgkmcnt(0)
	v_mfma_f32_32x32x16_bf16 v[0:15], v[38:41], v[136:139], v[0:15]
	s_nop 15
	s_nop 7
	s_cbranch_scc1 .LBB0_1275
	s_add_i32 s22, s88, s18
	s_cmpk_gt_i32 s22, 0xaf
	s_cselect_b64 s[22:23], -1, 0
	s_sub_i32 s30, 63, s18
	s_cmp_le_i32 s30, s88
	s_cselect_b64 s[30:31], -1, 0
	s_and_b64 s[22:23], s[30:31], s[22:23]
	s_and_b64 vcc, exec, s[22:23]
	s_cbranch_vccnz .LBB0_1275
; __device__ __forceinline__ void cmask(f32x16&p0,f32x16&p1,int jb,int qrel,int hi,lds_cfptr bt){
;   const lds_cfptr t=bt+(qrel-64*jb-4*hi+256);
;   const int dq=qrel-64*jb-4*hi;
;   #pragma unroll
;   for(int r=0;r<16;++r){const int off=(r&3)+8*(r>>2); const float b0=t[-off],b1=t[-off-32]; p0[r]=(dq-off<0)?(p0[r]-INFINITY):p0[r]+b0; p1[r]=(dq-off-32<0)?(p1[r]-INFINITY):p1[r]+b1;}
; }
	v_sub_u32_e32 v34, s18, v215
	v_add_u32_e32 v34, v234, v34
	v_lshl_add_u32 v37, v34, 2, s70
	ds_read_b32 v35, v37 offset:896
	v_cmp_lt_i32_e32 vcc, -1, v34
	v_mov_b32_e32 v36, 0xff800000
	v_mov_b32_e32 v38, 0xff800000
	s_and_saveexec_b64 s[50:51], vcc
	ds_read_b32 v38, v37 offset:1024
	s_or_b64 exec, exec, s[50:51]
	ds_read_b32 v39, v37 offset:892
	v_cmp_lt_i32_e32 vcc, 0, v34
	s_and_saveexec_b64 s[50:51], vcc
	ds_read_b32 v36, v37 offset:1020
	s_or_b64 exec, exec, s[50:51]
	ds_read_b32 v40, v37 offset:888
	v_cmp_lt_i32_e32 vcc, 1, v34
	v_mov_b32_e32 v41, 0xff800000
	v_mov_b32_e32 v42, 0xff800000
	s_and_saveexec_b64 s[50:51], vcc
	ds_read_b32 v42, v37 offset:1016
	s_or_b64 exec, exec, s[50:51]
	ds_read_b32 v43, v37 offset:884
	v_cmp_lt_i32_e32 vcc, 2, v34
	s_and_saveexec_b64 s[50:51], vcc
	ds_read_b32 v41, v37 offset:1012
	s_or_b64 exec, exec, s[50:51]
	ds_read_b32 v44, v37 offset:864
	v_cmp_lt_i32_e32 vcc, 7, v34
	v_mov_b32_e32 v45, 0xff800000
	v_mov_b32_e32 v46, 0xff800000
	s_and_saveexec_b64 s[50:51], vcc
	ds_read_b32 v46, v37 offset:992
	s_or_b64 exec, exec, s[50:51]
	ds_read_b32 v47, v37 offset:860
	v_cmp_lt_i32_e32 vcc, 8, v34
	s_and_saveexec_b64 s[50:51], vcc
	ds_read_b32 v45, v37 offset:988
	s_or_b64 exec, exec, s[50:51]
	ds_read_b32 v48, v37 offset:856
	v_cmp_lt_i32_e32 vcc, 9, v34
	v_mov_b32_e32 v49, 0xff800000
	v_mov_b32_e32 v50, 0xff800000
	s_and_saveexec_b64 s[50:51], vcc
	ds_read_b32 v50, v37 offset:984
	s_or_b64 exec, exec, s[50:51]
	ds_read_b32 v51, v37 offset:852
	v_cmp_lt_i32_e32 vcc, 10, v34
	s_and_saveexec_b64 s[50:51], vcc
	ds_read_b32 v49, v37 offset:980
	s_or_b64 exec, exec, s[50:51]
	ds_read_b32 v52, v37 offset:832
	v_cmp_lt_i32_e32 vcc, 15, v34
	v_mov_b32_e32 v53, 0xff800000
	v_mov_b32_e32 v54, 0xff800000
	s_and_saveexec_b64 s[50:51], vcc
	ds_read_b32 v54, v37 offset:960
	s_or_b64 exec, exec, s[50:51]
	ds_read_b32 v55, v37 offset:828
	v_cmp_lt_i32_e32 vcc, 16, v34
	s_and_saveexec_b64 s[50:51], vcc
	ds_read_b32 v53, v37 offset:956
	s_or_b64 exec, exec, s[50:51]
	ds_read_b32 v56, v37 offset:824
	v_cmp_lt_i32_e32 vcc, 17, v34
	v_mov_b32_e32 v57, 0xff800000
	v_mov_b32_e32 v58, 0xff800000
	s_and_saveexec_b64 s[50:51], vcc
	ds_read_b32 v58, v37 offset:952
	s_or_b64 exec, exec, s[50:51]
	ds_read_b32 v59, v37 offset:820
	v_cmp_lt_i32_e32 vcc, 18, v34
	s_and_saveexec_b64 s[50:51], vcc
	ds_read_b32 v57, v37 offset:948
	s_or_b64 exec, exec, s[50:51]
	ds_read_b32 v60, v37 offset:800
	v_cmp_lt_i32_e32 vcc, 23, v34
	v_mov_b32_e32 v61, 0xff800000
	v_mov_b32_e32 v62, 0xff800000
	s_and_saveexec_b64 s[50:51], vcc
	ds_read_b32 v62, v37 offset:928
	s_or_b64 exec, exec, s[50:51]
	ds_read_b32 v63, v37 offset:796
	v_cmp_lt_i32_e32 vcc, 24, v34
	s_and_saveexec_b64 s[50:51], vcc
	ds_read_b32 v61, v37 offset:924
	s_or_b64 exec, exec, s[50:51]
	ds_read_b32 v65, v37 offset:792
	v_cmp_lt_i32_e32 vcc, 25, v34
	v_mov_b32_e32 v66, 0xff800000
	v_mov_b32_e32 v67, 0xff800000
	s_and_saveexec_b64 s[50:51], vcc
	ds_read_b32 v67, v37 offset:920
	s_or_b64 exec, exec, s[50:51]
	ds_read_b32 v64, v37 offset:788
	v_cmp_lt_i32_e32 vcc, 26, v34
	s_and_saveexec_b64 s[50:51], vcc
	ds_read_b32 v66, v37 offset:916
	s_or_b64 exec, exec, s[50:51]
	v_cmp_lt_i32_e32 vcc, 31, v34
	s_waitcnt lgkmcnt(14)
	v_add_f32_e32 v16, v16, v38
	v_add_f32_e32 v17, v17, v36
	v_cndmask_b32_e32 v35, v232, v35, vcc
	v_cmp_lt_i32_e32 vcc, 32, v34
	v_add_f32_e32 v0, v0, v35
	s_waitcnt lgkmcnt(13)
	v_add_f32_e32 v18, v18, v42
	v_cndmask_b32_e32 v35, v232, v39, vcc
	v_cmp_lt_i32_e32 vcc, 33, v34
	v_add_f32_e32 v1, v1, v35
	s_waitcnt lgkmcnt(12)
	v_add_f32_e32 v19, v19, v41
	v_cndmask_b32_e32 v35, v232, v40, vcc
	v_cmp_lt_i32_e32 vcc, 34, v34
	v_add_f32_e32 v2, v2, v35
	s_waitcnt lgkmcnt(11)
	v_add_f32_e32 v20, v20, v46
	v_cndmask_b32_e32 v35, v232, v43, vcc
	v_cmp_lt_i32_e32 vcc, 39, v34
	v_add_f32_e32 v3, v3, v35
	s_waitcnt lgkmcnt(10)
	v_add_f32_e32 v21, v21, v45
	v_cndmask_b32_e32 v35, v232, v44, vcc
	v_cmp_lt_i32_e32 vcc, 40, v34
	v_add_f32_e32 v4, v4, v35
	s_waitcnt lgkmcnt(9)
	v_add_f32_e32 v22, v22, v50
	v_cndmask_b32_e32 v35, v232, v47, vcc
	v_cmp_lt_i32_e32 vcc, 41, v34
	v_add_f32_e32 v5, v5, v35
	s_waitcnt lgkmcnt(8)
	v_add_f32_e32 v23, v23, v49
	v_cndmask_b32_e32 v35, v232, v48, vcc
	v_cmp_lt_i32_e32 vcc, 42, v34
	v_add_f32_e32 v6, v6, v35
	s_waitcnt lgkmcnt(7)
	v_add_f32_e32 v24, v24, v54
	v_cndmask_b32_e32 v35, v232, v51, vcc
	v_cmp_lt_i32_e32 vcc, 47, v34
	v_add_f32_e32 v7, v7, v35
	s_waitcnt lgkmcnt(6)
	v_add_f32_e32 v25, v25, v53
	v_cndmask_b32_e32 v35, v232, v52, vcc
	v_cmp_lt_i32_e32 vcc, 48, v34
	v_add_f32_e32 v8, v8, v35
	s_waitcnt lgkmcnt(5)
	v_add_f32_e32 v26, v26, v58
	v_cndmask_b32_e32 v35, v232, v55, vcc
	v_cmp_lt_i32_e32 vcc, 49, v34
	v_add_f32_e32 v9, v9, v35
	s_waitcnt lgkmcnt(4)
	v_add_f32_e32 v27, v27, v57
	v_cndmask_b32_e32 v35, v232, v56, vcc
	v_cmp_lt_i32_e32 vcc, 50, v34
	v_add_f32_e32 v10, v10, v35
	s_waitcnt lgkmcnt(3)
	v_add_f32_e32 v28, v28, v62
	v_cndmask_b32_e32 v35, v232, v59, vcc
	v_cmp_lt_i32_e32 vcc, 55, v34
	v_add_f32_e32 v11, v11, v35
	s_waitcnt lgkmcnt(2)
	v_add_f32_e32 v29, v29, v61
	v_cndmask_b32_e32 v35, v232, v60, vcc
	v_cmp_lt_i32_e32 vcc, 56, v34
	v_add_f32_e32 v12, v12, v35
	s_waitcnt lgkmcnt(1)
	v_add_f32_e32 v30, v30, v67
	v_cndmask_b32_e32 v35, v232, v63, vcc
	v_cmp_lt_i32_e32 vcc, 57, v34
	v_add_f32_e32 v13, v13, v35
	s_waitcnt lgkmcnt(0)
	v_add_f32_e32 v31, v31, v66
	v_cndmask_b32_e32 v35, v232, v65, vcc
	v_cmp_lt_i32_e32 vcc, 58, v34
	v_add_f32_e32 v14, v14, v35
	s_nop 0
	v_cndmask_b32_e32 v34, v232, v64, vcc
	v_add_f32_e32 v15, v15, v34

; __host__ __device__ __forceinline__ size_t tiled_off(int row, int col, int K) { return ((size_t)(row >> 7) * (K >> 6) + (col >> 6)) * 8192 + (lds_byte(row & 127, col & 63) >> 1); }
; __device__ __forceinline__ void combine_local(const Args& a, int vcu, int wave, int lane) {
;     constexpr float LINIT = 0.35550906759f;
;     bf16* O0 = (bf16*)(a.ws + WS_HBA); const bf16* O1 = (const bf16*)(a.ws + WS_O1);
;     const float d1 = wave_sum(a.in[I_LQ1][lane] * a.in[I_LK1][lane]), d2 = wave_sum(a.in[I_LQ2][lane] * a.in[I_LK2][lane]);
;     const float lam = __expf(d1) - __expf(d2) + LINIT;
;     float g[16];
; #pragma unroll
;     for (int e = 0; e < 16; ++e) g[e] = a.in[I_ASG][(lane & 7) * 16 + e] * (1.0f - LINIT);
;     const int p = vcu >> 3, b = p >> 3, h = p & 7, s = vcu & 7;
; #pragma unroll 1
;     for (int k = 0; k < 4; ++k) { const int qb = (k == 0) ? s : (k == 1) ? 15 - s : (k == 2) ? 16 + s : 31 - s;
; #pragma unroll 2
;         for (int it = 0; it < 4; ++it) { const size_t off = pg8::tiled_off(b * SEQ + 256 * qb + 32 * wave + 8 * it + (lane >> 3), h * 128 + (lane & 7) * 16, D);
;             const v4u* p0 = (const v4u*)(O0 + off); const v4u* p1 = (const v4u*)(O1 + off);
;             const v4u a0 = p0[0], a1 = p0[1], b0 = p1[0], b1 = p1[1];
;             const unsigned aw[8] = {a0.x, a0.y, a0.z, a0.w, a1.x, a1.y, a1.z, a1.w}, bw[8] = {b0.x, b0.y, b0.z, b0.w, b1.x, b1.y, b1.z, b1.w};
;             float o[16]; float ssq = 0.f;
; #pragma unroll
;             for (int e = 0; e < 8; ++e) { o[2 * e] = __uint_as_float(aw[e] << 16) - lam * __uint_as_float(bw[e] << 16); o[2 * e + 1] = __uint_as_float(aw[e] & 0xffff0000u) - lam * __uint_as_float(bw[e] & 0xffff0000u);
;                 ssq += o[2 * e] * o[2 * e] + o[2 * e + 1] * o[2 * e + 1]; }
;             ssq += __shfl_xor(ssq, 1); ssq += __shfl_xor(ssq, 2); ssq += __shfl_xor(ssq, 4);
;             const float r = __builtin_amdgcn_rsqf(ssq * (1.0f / 128.0f) + 1e-6f);
; __global__ void __launch_bounds__(NWAVES * 64, 2) mega_fwd(Args args) {
;     ...
;         asm volatile("s_waitcnt vmcnt(0)" ::: "memory"); __builtin_amdgcn_fence(__ATOMIC_ACQ_REL, "workgroup"); __syncthreads();
;         combine_local(args, vcu, wave, lane);
.LBB0_1453:
	s_setprio 0
	v_readlane_b32 s40, v252, 27
	v_lshlrev_b32_e32 v0, 2, v209
	v_readlane_b32 s41, v252, 28
	v_readlane_b32 s42, v252, 29
	v_readlane_b32 s43, v252, 30
	v_readlane_b32 s44, v252, 31
	v_readlane_b32 s45, v252, 32
	v_readlane_b32 s46, v252, 33
	v_readlane_b32 s47, v252, 34
	v_readlane_b32 s48, v252, 35
	v_readlane_b32 s49, v252, 36
	v_readlane_b32 s50, v252, 37
	v_readlane_b32 s51, v252, 38
	v_readlane_b32 s52, v252, 39
	v_readlane_b32 s53, v252, 40
	v_readlane_b32 s54, v252, 41
	v_readlane_b32 s55, v252, 42
	s_waitcnt vmcnt(0)
	s_barrier
	s_mov_b64 s[22:23], s[54:55]
	s_nop 2
	global_load_dword v1, v0, s[54:55]
	v_readlane_b32 s40, v252, 43
	v_readlane_b32 s41, v252, 44
	v_readlane_b32 s42, v252, 45
	v_readlane_b32 s43, v252, 46
	v_readlane_b32 s44, v252, 47
	v_readlane_b32 s45, v252, 48
	v_readlane_b32 s46, v252, 49
	v_readlane_b32 s47, v252, 50
	s_mov_b64 s[12:13], s[40:41]
	s_mov_b64 s[14:15], s[42:43]
	s_mov_b64 s[16:17], s[44:45]
	global_load_dword v20, v0, s[12:13]
	global_load_dword v22, v0, s[14:15]
	global_load_dword v23, v0, s[16:17]
	v_and_b32_e32 v0, 0x70, v211
	s_mov_b64 s[18:19], s[46:47]
	v_lshlrev_b32_e32 v0, 2, v0
	global_load_dwordx4 v[2:5], v0, s[18:19]
	global_load_dwordx4 v[6:9], v0, s[18:19] offset:16
	global_load_dwordx4 v[10:13], v0, s[18:19] offset:32
	global_load_dwordx4 v[14:17], v0, s[18:19] offset:48
	v_mbcnt_lo_u32_b32 v0, -1, 0
	v_lshlrev_b32_e32 v18, 11, v208
	v_mbcnt_hi_u32_b32 v27, -1, v0
	v_lshlrev_b32_e32 v19, 5, v208
	v_and_b32_e32 v0, 0x2000, v18
	v_and_b32_e32 v18, 64, v27
	v_and_b32_e32 v25, 32, v19
	v_xor_b32_e32 v19, 1, v27
	v_add_u32_e32 v18, 64, v18
	v_xor_b32_e32 v28, 2, v27
	v_cmp_lt_i32_e32 vcc, v19, v18
	v_xor_b32_e32 v29, 4, v27
	v_xor_b32_e32 v30, 8, v27
	v_cndmask_b32_e32 v19, v27, v19, vcc
	v_cmp_lt_i32_e32 vcc, v28, v18
	v_xor_b32_e32 v31, 16, v27
	v_xor_b32_e32 v32, 32, v27
	v_cndmask_b32_e32 v28, v27, v28, vcc
	v_cmp_lt_i32_e32 vcc, v29, v18
	v_lshlrev_b32_e32 v28, 2, v28
	v_readlane_b32 s12, v252, 6
	v_cndmask_b32_e32 v29, v27, v29, vcc
	v_cmp_lt_i32_e32 vcc, v30, v18
	v_lshlrev_b32_e32 v29, 2, v29
	s_lshl_b32 s1, s12, 7
	v_cndmask_b32_e32 v30, v27, v30, vcc
	v_cmp_lt_i32_e32 vcc, v31, v18
	s_mov_b32 s0, 0x3f24fd5c
	s_and_b32 s1, s1, 0xffffe000
	v_cndmask_b32_e32 v31, v27, v31, vcc
	v_cmp_lt_i32_e32 vcc, v32, v18
	v_lshlrev_b32_e32 v34, 2, v31
	v_readlane_b32 s13, v252, 59
	v_cndmask_b32_e32 v18, v27, v32, vcc
	v_lshlrev_b32_e32 v27, 2, v19
	v_lshlrev_b32_e32 v32, 2, v30
	v_lshlrev_b32_e32 v35, 2, v18
	s_lshl_b32 s18, s12, 13
	s_lshl_b32 s14, s12, 11
	s_lshl_b32 s19, s13, 11
	s_and_b32 s18, s18, 0xfff80000
	s_and_b32 s3, s12, 7
	s_lshl_b32 s17, s13, 5
	s_and_b32 s21, s14, 0x1c000
	s_add_i32 s18, s18, s19
	s_mov_b32 s2, 0
	v_bfe_u32 v21, v208, 1, 1
	s_movk_i32 s12, 0x3c0
	s_mov_b32 s13, 0xffff0000
	v_mov_b32_e32 v24, 0x358637bd
	s_xor_b32 s14, s3, 15
	s_or_b32 s15, s3, 16
	s_xor_b32 s16, s3, 31
	s_add_i32 s17, s1, s17
	v_or_b32_e32 v0, s21, v0
	v_lshl_or_b32 v26, v210, 6, s18
	s_movk_i32 s18, 0x7fff
	v_readlane_b32 s48, v252, 51
	v_readlane_b32 s49, v252, 52
	v_readlane_b32 s50, v252, 53
	v_readlane_b32 s51, v252, 54
	v_readlane_b32 s52, v252, 55
	v_readlane_b32 s53, v252, 56
	v_readlane_b32 s54, v252, 57
	v_readlane_b32 s55, v252, 58
	s_waitcnt vmcnt(6)
	v_mul_f32_e32 v19, v1, v20
	ds_bpermute_b32 v31, v27, v19
	s_waitcnt vmcnt(4)
	v_mul_f32_e32 v30, v22, v23
	ds_bpermute_b32 v30, v27, v30
	s_waitcnt vmcnt(3)
	v_mov_b32_e32 v18, v2
	v_mov_b32_e32 v19, v4
	s_waitcnt lgkmcnt(1)
	v_fmac_f32_e32 v31, v1, v20
	ds_bpermute_b32 v1, v28, v31
	s_waitcnt lgkmcnt(1)
	v_fmac_f32_e32 v30, v22, v23
	ds_bpermute_b32 v2, v28, v30
	v_mov_b32_e32 v4, v3
	s_waitcnt vmcnt(2)
	v_mov_b32_e32 v22, v6
	s_waitcnt lgkmcnt(1)
	v_add_f32_e32 v1, v31, v1
	ds_bpermute_b32 v3, v29, v1
	s_waitcnt lgkmcnt(1)
	v_add_f32_e32 v2, v30, v2
	ds_bpermute_b32 v6, v29, v2
	v_mov_b32_e32 v23, v8
	v_mov_b32_e32 v8, v7
	s_waitcnt lgkmcnt(1)
	v_add_f32_e32 v1, v1, v3
	ds_bpermute_b32 v3, v32, v1
	s_waitcnt lgkmcnt(1)
	v_add_f32_e32 v2, v2, v6
	ds_bpermute_b32 v6, v32, v2
	s_waitcnt vmcnt(1)
	v_mov_b32_e32 v30, v10
	s_waitcnt vmcnt(0)
	v_mov_b32_e32 v32, v14
	s_waitcnt lgkmcnt(1)
	v_add_f32_e32 v1, v1, v3
	ds_bpermute_b32 v7, v34, v1
	s_waitcnt lgkmcnt(1)
	v_add_f32_e32 v6, v2, v6
	ds_bpermute_b32 v10, v34, v6
	v_mov_b32_e32 v33, v16
	v_mov_b32_e32 v16, v15
	s_waitcnt lgkmcnt(1)
	v_add_f32_e32 v1, v1, v7
	v_pk_mul_f32 v[2:3], v[18:19], s[0:1] op_sel_hi:[1,0]
	s_waitcnt lgkmcnt(0)
	v_add_f32_e32 v14, v6, v10
	ds_bpermute_b32 v15, v35, v1
	ds_bpermute_b32 v18, v35, v14
	v_mov_b32_e32 v31, v12
	v_mov_b32_e32 v12, v11
	v_pk_mul_f32 v[4:5], v[4:5], s[0:1] op_sel_hi:[1,0]
	s_waitcnt lgkmcnt(1)
	v_add_f32_e32 v1, v1, v15
	s_waitcnt lgkmcnt(0)
	v_add_f32_e32 v14, v14, v18
	v_mul_f32_e32 v1, 0x3fb8aa3b, v1
	v_mul_f32_e32 v14, 0x3fb8aa3b, v14
	v_exp_f32_e32 v1, v1
	v_exp_f32_e32 v18, v14
	v_pk_mul_f32 v[6:7], v[22:23], s[0:1] op_sel_hi:[1,0]
	v_pk_mul_f32 v[8:9], v[8:9], s[0:1] op_sel_hi:[1,0]
	v_pk_mul_f32 v[10:11], v[30:31], s[0:1] op_sel_hi:[1,0]
	v_sub_f32_e32 v1, v1, v18
	v_add_f32_e32 v18, 0x3eb60549, v1
	v_pk_mul_f32 v[12:13], v[12:13], s[0:1] op_sel_hi:[1,0]
	v_pk_mul_f32 v[14:15], v[32:33], s[0:1] op_sel_hi:[1,0]
	v_pk_mul_f32 v[16:17], v[16:17], s[0:1] op_sel_hi:[1,0]
	v_mov_b32_e32 v19, v18
